# relu2 GEMM: MFMA A/B operands swapped so accumulators are C^T fragments; epilogue = 16 dwordx2 stores via v_cvt_pk_bf16 instead of 64 short stores
# baseline (speedup 1.0000x reference)
.LBB0_80:
	v_and_b32_e32 v66, 0xc0, v125
	v_lshrrev_b32_e32 v67, 1, v0
	v_add3_u32 v66, v66, v67, s26
	v_ashrrev_i32_e32 v67, 31, v66
	v_lshlrev_b64 v[66:67], 13, v[66:67]
	v_and_b32_e32 v68, 12, v125
	v_lshl_add_u64 v[66:67], s[0:1], 0, v[66:67]
	v_lshlrev_b32_e32 v68, 1, v68
	v_lshl_add_u64 v[66:67], s[22:23], 1, v[66:67]
	v_mov_b32_e32 v69, 0
	v_lshl_add_u64 v[66:67], v[66:67], 0, s[20:21]
	s_mov_b64 s[16:17], 0x20000
	v_lshl_add_u64 v[66:67], v[66:67], 0, v[68:69]
	v_lshl_add_u64 v[68:69], v[66:67], 0, s[16:17]
	v_lshl_add_u64 v[70:71], v[68:69], 0, s[16:17]
	v_lshl_add_u64 v[72:73], v[70:71], 0, s[16:17]
	v_max_f32_e32 v62, 0, v62
	v_max_f32_e32 v63, 0, v63
	v_max_f32_e32 v64, 0, v64
	v_max_f32_e32 v65, 0, v65
	v_pk_mul_f32 v[62:63], v[62:63], v[62:63]
	v_pk_mul_f32 v[64:65], v[64:65], v[64:65]
	v_cvt_pk_bf16_f32 v62, v62, v63
	v_cvt_pk_bf16_f32 v63, v64, v65
	global_store_dwordx2 v[66:67], v[62:63], off
	v_max_f32_e32 v58, 0, v58
	v_max_f32_e32 v59, 0, v59
	v_max_f32_e32 v60, 0, v60
	v_max_f32_e32 v61, 0, v61
	v_pk_mul_f32 v[58:59], v[58:59], v[58:59]
	v_pk_mul_f32 v[60:61], v[60:61], v[60:61]
	v_cvt_pk_bf16_f32 v58, v58, v59
	v_cvt_pk_bf16_f32 v59, v60, v61
	global_store_dwordx2 v[66:67], v[58:59], off offset:32
	v_max_f32_e32 v54, 0, v54
	v_max_f32_e32 v55, 0, v55
	v_max_f32_e32 v56, 0, v56
	v_max_f32_e32 v57, 0, v57
	v_pk_mul_f32 v[54:55], v[54:55], v[54:55]
	v_pk_mul_f32 v[56:57], v[56:57], v[56:57]
	v_cvt_pk_bf16_f32 v54, v54, v55
	v_cvt_pk_bf16_f32 v55, v56, v57
	global_store_dwordx2 v[66:67], v[54:55], off offset:64
	v_max_f32_e32 v50, 0, v50
	v_max_f32_e32 v51, 0, v51
	v_max_f32_e32 v52, 0, v52
	v_max_f32_e32 v53, 0, v53
	v_pk_mul_f32 v[50:51], v[50:51], v[50:51]
	v_pk_mul_f32 v[52:53], v[52:53], v[52:53]
	v_cvt_pk_bf16_f32 v50, v50, v51
	v_cvt_pk_bf16_f32 v51, v52, v53
	global_store_dwordx2 v[66:67], v[50:51], off offset:96
	v_max_f32_e32 v46, 0, v46
	v_max_f32_e32 v47, 0, v47
	v_max_f32_e32 v48, 0, v48
	v_max_f32_e32 v49, 0, v49
	v_pk_mul_f32 v[46:47], v[46:47], v[46:47]
	v_pk_mul_f32 v[48:49], v[48:49], v[48:49]
	v_cvt_pk_bf16_f32 v46, v46, v47
	v_cvt_pk_bf16_f32 v47, v48, v49
	global_store_dwordx2 v[68:69], v[46:47], off
	v_max_f32_e32 v42, 0, v42
	v_max_f32_e32 v43, 0, v43
	v_max_f32_e32 v44, 0, v44
	v_max_f32_e32 v45, 0, v45
	v_pk_mul_f32 v[42:43], v[42:43], v[42:43]
	v_pk_mul_f32 v[44:45], v[44:45], v[44:45]
	v_cvt_pk_bf16_f32 v42, v42, v43
	v_cvt_pk_bf16_f32 v43, v44, v45
	global_store_dwordx2 v[68:69], v[42:43], off offset:32
	v_max_f32_e32 v38, 0, v38
	v_max_f32_e32 v39, 0, v39
	v_max_f32_e32 v40, 0, v40
	v_max_f32_e32 v41, 0, v41
	v_pk_mul_f32 v[38:39], v[38:39], v[38:39]
	v_pk_mul_f32 v[40:41], v[40:41], v[40:41]
	v_cvt_pk_bf16_f32 v38, v38, v39
	v_cvt_pk_bf16_f32 v39, v40, v41
	global_store_dwordx2 v[68:69], v[38:39], off offset:64
	v_max_f32_e32 v34, 0, v34
	v_max_f32_e32 v35, 0, v35
	v_max_f32_e32 v36, 0, v36
	v_max_f32_e32 v37, 0, v37
	v_pk_mul_f32 v[34:35], v[34:35], v[34:35]
	v_pk_mul_f32 v[36:37], v[36:37], v[36:37]
	v_cvt_pk_bf16_f32 v34, v34, v35
	v_cvt_pk_bf16_f32 v35, v36, v37
	global_store_dwordx2 v[68:69], v[34:35], off offset:96
	v_max_f32_e32 v30, 0, v30
	v_max_f32_e32 v31, 0, v31
	v_max_f32_e32 v32, 0, v32
	v_max_f32_e32 v33, 0, v33
	v_pk_mul_f32 v[30:31], v[30:31], v[30:31]
	v_pk_mul_f32 v[32:33], v[32:33], v[32:33]
	v_cvt_pk_bf16_f32 v30, v30, v31
	v_cvt_pk_bf16_f32 v31, v32, v33
	global_store_dwordx2 v[70:71], v[30:31], off
	v_max_f32_e32 v26, 0, v26
	v_max_f32_e32 v27, 0, v27
	v_max_f32_e32 v28, 0, v28
	v_max_f32_e32 v29, 0, v29
	v_pk_mul_f32 v[26:27], v[26:27], v[26:27]
	v_pk_mul_f32 v[28:29], v[28:29], v[28:29]
	v_cvt_pk_bf16_f32 v26, v26, v27
	v_cvt_pk_bf16_f32 v27, v28, v29
	global_store_dwordx2 v[70:71], v[26:27], off offset:32
	v_max_f32_e32 v22, 0, v22
	v_max_f32_e32 v23, 0, v23
	v_max_f32_e32 v24, 0, v24
	v_max_f32_e32 v25, 0, v25
	v_pk_mul_f32 v[22:23], v[22:23], v[22:23]
	v_pk_mul_f32 v[24:25], v[24:25], v[24:25]
	v_cvt_pk_bf16_f32 v22, v22, v23
	v_cvt_pk_bf16_f32 v23, v24, v25
	global_store_dwordx2 v[70:71], v[22:23], off offset:64
	v_max_f32_e32 v18, 0, v18
	v_max_f32_e32 v19, 0, v19
	v_max_f32_e32 v20, 0, v20
	v_max_f32_e32 v21, 0, v21
	v_pk_mul_f32 v[18:19], v[18:19], v[18:19]
	v_pk_mul_f32 v[20:21], v[20:21], v[20:21]
	v_cvt_pk_bf16_f32 v18, v18, v19
	v_cvt_pk_bf16_f32 v19, v20, v21
	global_store_dwordx2 v[70:71], v[18:19], off offset:96
	v_max_f32_e32 v14, 0, v14
	v_max_f32_e32 v15, 0, v15
	v_max_f32_e32 v16, 0, v16
	v_max_f32_e32 v17, 0, v17
	v_pk_mul_f32 v[14:15], v[14:15], v[14:15]
	v_pk_mul_f32 v[16:17], v[16:17], v[16:17]
	v_cvt_pk_bf16_f32 v14, v14, v15
	v_cvt_pk_bf16_f32 v15, v16, v17
	global_store_dwordx2 v[72:73], v[14:15], off
	v_max_f32_e32 v10, 0, v10
	v_max_f32_e32 v11, 0, v11
	v_max_f32_e32 v12, 0, v12
	v_max_f32_e32 v13, 0, v13
	v_pk_mul_f32 v[10:11], v[10:11], v[10:11]
	v_pk_mul_f32 v[12:13], v[12:13], v[12:13]
	v_cvt_pk_bf16_f32 v10, v10, v11
	v_cvt_pk_bf16_f32 v11, v12, v13
	global_store_dwordx2 v[72:73], v[10:11], off offset:32
	v_max_f32_e32 v6, 0, v6
	v_max_f32_e32 v7, 0, v7
	v_max_f32_e32 v8, 0, v8
	v_max_f32_e32 v9, 0, v9
	v_pk_mul_f32 v[6:7], v[6:7], v[6:7]
	v_pk_mul_f32 v[8:9], v[8:9], v[8:9]
	v_cvt_pk_bf16_f32 v6, v6, v7
	v_cvt_pk_bf16_f32 v7, v8, v9
	global_store_dwordx2 v[72:73], v[6:7], off offset:64
	v_max_f32_e32 v2, 0, v2
	v_max_f32_e32 v3, 0, v3
	v_max_f32_e32 v4, 0, v4
	v_max_f32_e32 v5, 0, v5
	v_pk_mul_f32 v[2:3], v[2:3], v[2:3]
	v_pk_mul_f32 v[4:5], v[4:5], v[4:5]
	v_cvt_pk_bf16_f32 v2, v2, v3
	v_cvt_pk_bf16_f32 v3, v4, v5
	global_store_dwordx2 v[72:73], v[2:3], off offset:96
	s_mov_b64 s[38:39], -1
	s_and_b64 vcc, exec, s[34:35]
	s_cbranch_vccnz .LBB0_89

.LBB0_84:
	s_mul_hi_u32 s34, s27, 0xaaaaaaab
	s_lshr_b32 s34, s34, 1
	s_mul_i32 s34, s34, 0x24000
	s_waitcnt lgkmcnt(0)
	v_mfma_f32_16x16x32_bf16 v[82:85], v[22:25], v[26:29], v[82:85]
	v_add_u32_e32 v191, s14, v99
	s_mul_hi_u32 s35, s19, 0xaaaaaaab
	s_lshr_b32 s35, s35, 1
	v_mfma_f32_16x16x32_bf16 v[78:81], v[18:21], v[26:29], v[78:81]
	s_mul_i32 s35, s35, 0x24000
	v_subrev_u32_e32 v180, s35, v128
	v_subrev_u32_e32 v181, s35, v129
	v_mfma_f32_16x16x32_bf16 v[74:77], v[10:13], v[26:29], v[74:77]
	v_subrev_u32_e32 v182, s35, v130
	v_mfma_f32_16x16x32_bf16 v[70:73], v[6:9], v[26:29], v[70:73]
	v_subrev_u32_e32 v26, s34, v127
	v_mfma_f32_16x16x32_bf16 v[66:69], v[22:25], v[14:17], v[66:69]
	v_mfma_f32_16x16x32_bf16 v[62:65], v[18:21], v[14:17], v[62:65]
	v_mfma_f32_16x16x32_bf16 v[58:61], v[10:13], v[14:17], v[58:61]
	v_mfma_f32_16x16x32_bf16 v[54:57], v[6:9], v[14:17], v[54:57]
	v_subrev_u32_e32 v14, s34, v131
	v_add_u32_e32 v16, v191, v26
	v_add_u32_e32 v14, v191, v14
	v_mfma_f32_16x16x32_bf16 v[38:41], v[22:25], v[30:33], v[38:41]
	v_subrev_u32_e32 v15, s35, v132
	v_mfma_f32_16x16x32_bf16 v[50:53], v[22:25], v[2:5], v[50:53]
	ds_read_b128 v[22:25], v16
	ds_read_b128 v[176:179], v16 offset:2048
	ds_read_b128 v[202:205], v16 offset:4096
	ds_read_b128 v[206:209], v16 offset:6144
	ds_read_b128 v[210:213], v14 offset:32768
	ds_read_b128 v[214:217], v14 offset:34816
	ds_read_b128 v[218:221], v14 offset:36864
	ds_read_b128 v[222:225], v14 offset:38912
	v_mfma_f32_16x16x32_bf16 v[90:93], v[18:21], v[30:33], v[90:93]
	v_mfma_f32_16x16x32_bf16 v[86:89], v[10:13], v[30:33], v[86:89]
	v_mfma_f32_16x16x32_bf16 v[94:97], v[6:9], v[30:33], v[94:97]
	v_mfma_f32_16x16x32_bf16 v[46:49], v[18:21], v[2:5], v[46:49]
	v_mfma_f32_16x16x32_bf16 v[42:45], v[10:13], v[2:5], v[42:45]
	v_mfma_f32_16x16x32_bf16 v[34:37], v[6:9], v[2:5], v[34:37]
	s_add_i32 s34, s6, 4
	s_mul_i32 s35, s34, 0xab
	s_bfe_u32 s35, s35, 0x70009
	s_mul_i32 s35, s35, 3
	s_sub_i32 s34, s34, s35
	s_and_b32 s34, s34, 0xff
	s_mul_i32 s36, s34, 0xc000
	s_waitcnt vmcnt(6)
	v_add_u32_e32 v2, v191, v15
	v_add_u32_e32 v6, v191, v182
	s_waitcnt lgkmcnt(0)
	v_mfma_f32_16x16x32_bf16 v[82:85], v[210:213], v[176:179], v[82:85]
	s_add_i32 s34, s36, s8
	s_waitcnt lgkmcnt(0)
	s_barrier
	v_mfma_f32_16x16x32_bf16 v[78:81], v[214:217], v[176:179], v[78:81]
	ds_read_b128 v[30:33], v2
	ds_read_b128 v[26:29], v2 offset:2048
	ds_read_b128 v[14:17], v2 offset:4096
	ds_read_b128 v[2:5], v2 offset:6144
	v_add_u32_e32 v7, v191, v181
	v_mfma_f32_16x16x32_bf16 v[74:77], v[218:221], v[176:179], v[74:77]
	s_mov_b32 m0, s34
	s_add_i32 s36, s36, s9
	s_add_i32 s27, s27, 1
	v_mfma_f32_16x16x32_bf16 v[70:73], v[222:225], v[176:179], v[70:73]
	v_lshl_add_u64 v[176:177], v[116:117], 0, v[100:101]
	v_lshl_add_u64 v[178:179], v[176:177], 0, s[84:85]
	v_mfma_f32_16x16x32_bf16 v[38:41], v[210:213], v[22:25], v[38:41]
	v_mfma_f32_16x16x32_bf16 v[90:93], v[214:217], v[22:25], v[90:93]
	v_mfma_f32_16x16x32_bf16 v[86:89], v[218:221], v[22:25], v[86:89]
	v_mfma_f32_16x16x32_bf16 v[94:97], v[222:225], v[22:25], v[94:97]
	ds_read_b128 v[22:25], v6
	ds_read_b128 v[18:21], v7
	v_add_u32_e32 v6, v191, v180
	ds_read_b128 v[10:13], v6
	ds_read_b128 v[6:9], v6 offset:2048
	global_load_lds_dwordx4 v[178:179], off
	v_lshl_add_u64 v[178:179], v[176:177], 0, s[76:77]
	s_add_i32 m0, s34, 0x400
	v_mfma_f32_16x16x32_bf16 v[66:69], v[210:213], v[202:205], v[66:69]
	global_load_lds_dwordx4 v[178:179], off
	v_lshl_add_u64 v[178:179], v[176:177], 0, s[54:55]
	s_add_i32 m0, s34, 0x800
	v_lshl_add_u64 v[176:177], v[176:177], 0, s[68:69]
	global_load_lds_dwordx4 v[178:179], off
	s_add_i32 m0, s34, 0xc00
	s_mov_b64 s[34:35], 0x2300180
	global_load_lds_dwordx4 v[176:177], off
	v_lshl_add_u64 v[176:177], v[118:119], 0, v[100:101]
	v_lshl_add_u64 v[178:179], v[176:177], 0, s[34:35]
	s_add_i32 m0, s36, 0x8000
	s_mov_b64 s[34:35], 0x2304180
	global_load_lds_dwordx4 v[178:179], off
	v_lshl_add_u64 v[176:177], v[176:177], 0, s[34:35]
	s_add_i32 m0, s36, 0x8400
	v_mfma_f32_16x16x32_bf16 v[62:65], v[214:217], v[202:205], v[62:65]
	global_load_lds_dwordx4 v[176:177], off
	v_mfma_f32_16x16x32_bf16 v[58:61], v[218:221], v[202:205], v[58:61]
	v_mfma_f32_16x16x32_bf16 v[54:57], v[222:225], v[202:205], v[54:57]
	v_mfma_f32_16x16x32_bf16 v[50:53], v[210:213], v[206:209], v[50:53]
	v_mfma_f32_16x16x32_bf16 v[46:49], v[214:217], v[206:209], v[46:49]
	v_mfma_f32_16x16x32_bf16 v[42:45], v[218:221], v[206:209], v[42:45]
	v_mfma_f32_16x16x32_bf16 v[34:37], v[222:225], v[206:209], v[34:37]
	s_add_i32 s6, s6, 1
	s_add_i32 s14, s14, 0xc000
	s_add_i32 s19, s19, 1
	v_lshl_add_u64 v[116:117], v[116:117], 0, s[2:3]
	s_cmp_eq_u32 s14, 0x9c000
	v_lshl_add_u64 v[118:119], v[118:119], 0, s[2:3]
	s_cbranch_scc0 .LBB0_84
	s_waitcnt lgkmcnt(0)
	v_mfma_f32_16x16x32_bf16 v[38:41], v[22:25], v[30:33], v[38:41]
	v_mfma_f32_16x16x32_bf16 v[90:93], v[18:21], v[30:33], v[90:93]
	v_mfma_f32_16x16x32_bf16 v[86:89], v[10:13], v[30:33], v[86:89]
	v_mfma_f32_16x16x32_bf16 v[30:33], v[6:9], v[30:33], v[94:97]
	v_mfma_f32_16x16x32_bf16 v[82:85], v[22:25], v[26:29], v[82:85]
	v_mfma_f32_16x16x32_bf16 v[78:81], v[18:21], v[26:29], v[78:81]
	v_mfma_f32_16x16x32_bf16 v[74:77], v[10:13], v[26:29], v[74:77]
	v_mfma_f32_16x16x32_bf16 v[26:29], v[6:9], v[26:29], v[70:73]
	v_mfma_f32_16x16x32_bf16 v[66:69], v[22:25], v[14:17], v[66:69]
	v_mfma_f32_16x16x32_bf16 v[62:65], v[18:21], v[14:17], v[62:65]
	v_mfma_f32_16x16x32_bf16 v[58:61], v[10:13], v[14:17], v[58:61]
	v_mfma_f32_16x16x32_bf16 v[14:17], v[6:9], v[14:17], v[54:57]
	v_mfma_f32_16x16x32_bf16 v[22:25], v[22:25], v[2:5], v[50:53]
	v_mfma_f32_16x16x32_bf16 v[18:21], v[18:21], v[2:5], v[46:49]
	s_nop 2
	ds_read_b128 v[46:49], v163
	ds_read_b128 v[50:53], v164 offset:2048
	ds_read_b128 v[54:57], v164 offset:4096
	ds_read_b128 v[70:73], v164 offset:6144
	v_mfma_f32_16x16x32_bf16 v[10:13], v[10:13], v[2:5], v[42:45]
	s_nop 2
	ds_read_b128 v[42:45], v165 offset:32768
	ds_read_b128 v[94:97], v166 offset:34816
	ds_read_b128 v[116:119], v166 offset:36864
	ds_read_b128 v[176:179], v166 offset:38912
	v_mfma_f32_16x16x32_bf16 v[2:5], v[6:9], v[2:5], v[34:37]
	s_waitcnt lgkmcnt(0)
	v_mfma_f32_16x16x32_bf16 v[6:9], v[42:45], v[46:49], v[38:41]
	s_waitcnt vmcnt(6)
	s_waitcnt lgkmcnt(0)
	s_barrier
	v_mfma_f32_16x16x32_bf16 v[34:37], v[94:97], v[46:49], v[90:93]
	v_mfma_f32_16x16x32_bf16 v[38:41], v[116:119], v[46:49], v[86:89]
	s_nop 1
	v_add_u32_e32 v90, 0x20800, v161
	v_mfma_f32_16x16x32_bf16 v[30:33], v[176:179], v[46:49], v[30:33]
	v_mfma_f32_16x16x32_bf16 v[46:49], v[42:45], v[50:53], v[82:85]
	v_mfma_f32_16x16x32_bf16 v[78:81], v[94:97], v[50:53], v[78:81]
	v_mfma_f32_16x16x32_bf16 v[74:77], v[116:119], v[50:53], v[74:77]
	v_mfma_f32_16x16x32_bf16 v[26:29], v[176:179], v[50:53], v[26:29]
	v_mfma_f32_16x16x32_bf16 v[50:53], v[42:45], v[54:57], v[66:69]
	v_mfma_f32_16x16x32_bf16 v[62:65], v[94:97], v[54:57], v[62:65]
	v_mfma_f32_16x16x32_bf16 v[58:61], v[116:119], v[54:57], v[58:61]
	v_mfma_f32_16x16x32_bf16 v[14:17], v[176:179], v[54:57], v[14:17]
	v_add_u32_e32 v54, v126, v120
	ds_read_b128 v[54:57], v54
	ds_read_b128 v[66:69], v167 offset:2048
	v_mfma_f32_16x16x32_bf16 v[18:21], v[94:97], v[70:73], v[18:21]
	v_add_u32_e32 v94, 0x21000, v161
	v_mfma_f32_16x16x32_bf16 v[10:13], v[116:119], v[70:73], v[10:13]
	v_add_u32_e32 v116, 0x21800, v161
	v_mfma_f32_16x16x32_bf16 v[22:25], v[42:45], v[70:73], v[22:25]
	ds_read_b128 v[42:45], v167 offset:4096
	ds_read_b128 v[82:85], v167 offset:6144
	ds_read_b128 v[86:89], v168
	ds_read_b128 v[90:93], v90
	ds_read_b128 v[94:97], v94
	ds_read_b128 v[116:119], v116
	v_mfma_f32_16x16x32_bf16 v[2:5], v[176:179], v[70:73], v[2:5]
	s_waitcnt lgkmcnt(0)
	v_mfma_f32_16x16x32_bf16 v[50:53], v[86:89], v[42:45], v[50:53]
	v_mfma_f32_16x16x32_bf16 v[62:65], v[90:93], v[42:45], v[62:65]
	v_mfma_f32_16x16x32_bf16 v[58:61], v[94:97], v[42:45], v[58:61]
	v_mfma_f32_16x16x32_bf16 v[14:17], v[116:119], v[42:45], v[14:17]
	v_add_u32_e32 v42, v126, v124
	v_mfma_f32_16x16x32_bf16 v[6:9], v[86:89], v[54:57], v[6:9]
	v_mfma_f32_16x16x32_bf16 v[34:37], v[90:93], v[54:57], v[34:37]
	v_mfma_f32_16x16x32_bf16 v[38:41], v[94:97], v[54:57], v[38:41]
	v_mfma_f32_16x16x32_bf16 v[30:33], v[116:119], v[54:57], v[30:33]
	v_mfma_f32_16x16x32_bf16 v[46:49], v[86:89], v[66:69], v[46:49]
	v_mfma_f32_16x16x32_bf16 v[54:57], v[90:93], v[66:69], v[78:81]
	v_mfma_f32_16x16x32_bf16 v[70:73], v[94:97], v[66:69], v[74:77]
	v_mfma_f32_16x16x32_bf16 v[26:29], v[116:119], v[66:69], v[26:29]
	ds_read_b128 v[42:45], v42
	ds_read_b128 v[66:69], v169
	ds_read_b128 v[74:77], v170
	ds_read_b128 v[78:81], v171
	v_mfma_f32_16x16x32_bf16 v[22:25], v[86:89], v[82:85], v[22:25]
	v_mfma_f32_16x16x32_bf16 v[18:21], v[90:93], v[82:85], v[18:21]
	v_mfma_f32_16x16x32_bf16 v[10:13], v[94:97], v[82:85], v[10:13]
	ds_read_b128 v[86:89], v172
	ds_read_b128 v[90:93], v173
	ds_read_b128 v[94:97], v174
	ds_read_b128 v[176:179], v175
	v_mfma_f32_16x16x32_bf16 v[2:5], v[116:119], v[82:85], v[2:5]
	s_waitcnt vmcnt(0)
	s_waitcnt lgkmcnt(0)
	v_mfma_f32_16x16x32_bf16 v[6:9], v[86:89], v[42:45], v[6:9]
	s_waitcnt lgkmcnt(0)
	s_barrier
	v_mfma_f32_16x16x32_bf16 v[34:37], v[90:93], v[42:45], v[34:37]
	v_mfma_f32_16x16x32_bf16 v[38:41], v[94:97], v[42:45], v[38:41]
	v_mfma_f32_16x16x32_bf16 v[30:33], v[176:179], v[42:45], v[30:33]
	v_mfma_f32_16x16x32_bf16 v[42:45], v[86:89], v[66:69], v[46:49]
	v_mfma_f32_16x16x32_bf16 v[46:49], v[90:93], v[66:69], v[54:57]
	v_mfma_f32_16x16x32_bf16 v[54:57], v[94:97], v[66:69], v[70:73]
	v_mfma_f32_16x16x32_bf16 v[26:29], v[176:179], v[66:69], v[26:29]
	v_mfma_f32_16x16x32_bf16 v[50:53], v[86:89], v[74:77], v[50:53]
	v_mfma_f32_16x16x32_bf16 v[62:65], v[90:93], v[74:77], v[62:65]
	v_mfma_f32_16x16x32_bf16 v[58:61], v[94:97], v[74:77], v[58:61]
	v_mfma_f32_16x16x32_bf16 v[14:17], v[176:179], v[74:77], v[14:17]
	ds_read_b128 v[66:69], v161 offset:38912
	ds_read_b128 v[70:73], v161 offset:36864
	ds_read_b128 v[74:77], v161 offset:34816
	ds_read_b128 v[82:85], v135 offset:32768
	v_mfma_f32_16x16x32_bf16 v[22:25], v[86:89], v[78:81], v[22:25]
	v_mfma_f32_16x16x32_bf16 v[18:21], v[90:93], v[78:81], v[18:21]
	v_mfma_f32_16x16x32_bf16 v[10:13], v[94:97], v[78:81], v[10:13]
	ds_read_b128 v[86:89], v134 offset:6144
	ds_read_b128 v[90:93], v134 offset:4096
	ds_read_b128 v[94:97], v134 offset:2048
	ds_read_b128 v[116:119], v133
	v_mfma_f32_16x16x32_bf16 v[2:5], v[176:179], v[78:81], v[2:5]
	s_waitcnt lgkmcnt(0)
	v_mfma_f32_16x16x32_bf16 v[78:81], v[74:77], v[94:97], v[46:49]
	s_nop 2
	v_add_u32_e32 v46, v105, v124
	v_mfma_f32_16x16x32_bf16 v[6:9], v[82:85], v[116:119], v[6:9]
	v_add_u32_e32 v47, v121, v124
	v_mfma_f32_16x16x32_bf16 v[34:37], v[74:77], v[116:119], v[34:37]
	v_mfma_f32_16x16x32_bf16 v[38:41], v[70:73], v[116:119], v[38:41]
	v_mfma_f32_16x16x32_bf16 v[30:33], v[66:69], v[116:119], v[30:33]
	v_mfma_f32_16x16x32_bf16 v[42:45], v[82:85], v[94:97], v[42:45]
	v_mfma_f32_16x16x32_bf16 v[116:119], v[70:73], v[94:97], v[54:57]
	v_mfma_f32_16x16x32_bf16 v[26:29], v[66:69], v[94:97], v[26:29]
	v_mfma_f32_16x16x32_bf16 v[94:97], v[82:85], v[90:93], v[50:53]
	v_mfma_f32_16x16x32_bf16 v[176:179], v[74:77], v[90:93], v[62:65]
	v_mfma_f32_16x16x32_bf16 v[202:205], v[70:73], v[90:93], v[58:61]
	v_mfma_f32_16x16x32_bf16 v[14:17], v[66:69], v[90:93], v[14:17]
	v_mfma_f32_16x16x32_bf16 v[82:85], v[82:85], v[86:89], v[22:25]
	s_nop 2
	ds_read_b128 v[22:25], v46
	ds_read_b128 v[90:93], v47 offset:2048
	v_add_u32_e32 v46, v122, v124
	v_mfma_f32_16x16x32_bf16 v[74:77], v[74:77], v[86:89], v[18:21]
	s_nop 2
	ds_read_b128 v[18:21], v47 offset:4096
	ds_read_b128 v[206:209], v47 offset:6144
	v_add_u32_e32 v47, v123, v124
	v_mfma_f32_16x16x32_bf16 v[70:73], v[70:73], v[86:89], v[10:13]
	s_nop 2
	ds_read_b128 v[10:13], v46 offset:32768
	ds_read_b128 v[210:213], v47 offset:34816
	ds_read_b128 v[214:217], v47 offset:36864
	ds_read_b128 v[218:221], v47 offset:38912
	v_mfma_f32_16x16x32_bf16 v[2:5], v[66:69], v[86:89], v[2:5]
	s_waitcnt lgkmcnt(0)
	v_mfma_f32_16x16x32_bf16 v[62:65], v[10:13], v[22:25], v[6:9]
	s_waitcnt vmcnt(0)
	s_waitcnt lgkmcnt(0)
	s_barrier
	v_mfma_f32_16x16x32_bf16 v[58:61], v[210:213], v[22:25], v[34:37]
	v_mfma_f32_16x16x32_bf16 v[54:57], v[214:217], v[22:25], v[38:41]
	v_mfma_f32_16x16x32_bf16 v[50:53], v[218:221], v[22:25], v[30:33]
	v_mfma_f32_16x16x32_bf16 v[46:49], v[10:13], v[90:93], v[42:45]
	v_mfma_f32_16x16x32_bf16 v[42:45], v[210:213], v[90:93], v[78:81]
	v_mfma_f32_16x16x32_bf16 v[38:41], v[214:217], v[90:93], v[116:119]
	v_mfma_f32_16x16x32_bf16 v[34:37], v[218:221], v[90:93], v[26:29]
	v_mfma_f32_16x16x32_bf16 v[30:33], v[10:13], v[18:21], v[94:97]
	v_mfma_f32_16x16x32_bf16 v[26:29], v[210:213], v[18:21], v[176:179]
	v_mfma_f32_16x16x32_bf16 v[22:25], v[214:217], v[18:21], v[202:205]
	v_mfma_f32_16x16x32_bf16 v[18:21], v[218:221], v[18:21], v[14:17]
	v_mfma_f32_16x16x32_bf16 v[14:17], v[10:13], v[206:209], v[82:85]
	v_mfma_f32_16x16x32_bf16 v[10:13], v[210:213], v[206:209], v[74:77]
	v_mfma_f32_16x16x32_bf16 v[6:9], v[214:217], v[206:209], v[70:73]
	v_mfma_f32_16x16x32_bf16 v[2:5], v[218:221], v[206:209], v[2:5]
	s_waitcnt lgkmcnt(0)
	s_barrier
	s_load_dword s6, s[78:79], 0x0
	s_waitcnt lgkmcnt(0)
	s_add_i32 s49, s6, s49
	s_cmpk_gt_i32 s49, 0x2ff
	s_cselect_b64 s[34:35], -1, 0
	s_cmpk_lt_i32 s49, 0x300
	s_cbranch_scc0 .LBB0_80
	s_mul_hi_i32 s6, s49, 0x2aaaaaab
	s_lshr_b32 s14, s6, 31
	s_ashr_i32 s6, s6, 2
	s_add_i32 s6, s6, s14
	s_mul_i32 s14, s6, 24
	s_sub_i32 s14, s49, s14
	v_lshl_add_u32 v66, s14, 8, v98
	v_ashrrev_i32_e32 v67, 31, v66
	v_lshlrev_b64 v[66:67], 11, v[66:67]
	s_mov_b32 m0, s8
	v_lshl_add_u64 v[66:67], v[108:109], 0, v[66:67]
	v_lshl_add_u32 v68, s6, 7, v104
	global_load_lds_dwordx4 v[66:67], off
	v_lshl_add_u64 v[70:71], v[66:67], 0, s[30:31]
	s_mov_b32 m0, s11
	v_ashrrev_i32_e32 v69, 31, v68
	global_load_lds_dwordx4 v[70:71], off
	v_lshl_add_u64 v[70:71], v[66:67], 0, s[24:25]
	s_add_i32 m0, s8, 0x800
	s_mov_b64 s[16:17], 0xc000
	v_lshlrev_b64 v[68:69], 11, v[68:69]
	global_load_lds_dwordx4 v[70:71], off
	v_lshl_add_u64 v[70:71], v[66:67], 0, s[16:17]
	s_mov_b32 m0, s12
	v_lshl_add_u64 v[68:69], v[110:111], 0, v[68:69]
	global_load_lds_dwordx4 v[70:71], off
	s_mov_b32 m0, s13
	v_lshl_add_u64 v[70:71], v[68:69], 0, s[30:31]
	global_load_lds_dwordx4 v[68:69], off
	s_mov_b32 m0, s40
	s_mov_b64 s[16:17], 0x4080
	global_load_lds_dwordx4 v[70:71], off
	v_lshl_add_u64 v[70:71], v[66:67], 0, s[2:3]
	s_add_i32 m0, s8, 0xc000
	s_mov_b64 s[36:37], 0x8080
	global_load_lds_dwordx4 v[70:71], off
	v_lshl_add_u64 v[70:71], v[66:67], 0, s[16:17]
	s_mov_b32 m0, s41
	s_mov_b64 s[38:39], 0x8100
	global_load_lds_dwordx4 v[70:71], off
	v_lshl_add_u64 v[70:71], v[66:67], 0, s[36:37]
	s_mov_b32 m0, s42
	s_mov_b64 s[36:37], 0xc080
	global_load_lds_dwordx4 v[70:71], off
	v_lshl_add_u64 v[70:71], v[66:67], 0, s[36:37]
	s_mov_b32 m0, s43
	s_mov_b64 s[36:37], 0x4100
	global_load_lds_dwordx4 v[70:71], off
	v_lshl_add_u64 v[70:71], v[68:69], 0, s[2:3]
	s_add_i32 m0, s9, 0x14000
	s_nop 0
	global_load_lds_dwordx4 v[70:71], off
	v_lshl_add_u64 v[70:71], v[68:69], 0, s[16:17]
	s_mov_b32 m0, s44
	s_mov_b64 s[16:17], 0x100
	global_load_lds_dwordx4 v[70:71], off
	v_lshl_add_u64 v[70:71], v[66:67], 0, s[16:17]
	s_add_i32 m0, s8, 0x18000
	s_nop 0
	global_load_lds_dwordx4 v[70:71], off
	v_lshl_add_u64 v[70:71], v[66:67], 0, s[36:37]
	s_mov_b32 m0, s45
	s_nop 0
	global_load_lds_dwordx4 v[70:71], off
	v_lshl_add_u64 v[70:71], v[66:67], 0, s[38:39]
	s_mov_b32 m0, s46
	s_mov_b64 s[38:39], 0xc100
	global_load_lds_dwordx4 v[70:71], off
	v_lshl_add_u64 v[66:67], v[66:67], 0, s[38:39]
	s_mov_b32 m0, s47
	s_nop 0
	global_load_lds_dwordx4 v[66:67], off
	v_lshl_add_u64 v[66:67], v[68:69], 0, s[16:17]
	s_add_i32 m0, s9, 0x20000
	s_nop 0
	global_load_lds_dwordx4 v[66:67], off
	v_lshl_add_u64 v[66:67], v[68:69], 0, s[36:37]
	s_mov_b32 m0, s48
	s_nop 0
	global_load_lds_dwordx4 v[66:67], off
	s_branch .LBB0_80
